# v38 with the whole instruction stream shifted by 24 bytes (6 s_nop at entry): code placement trial
# speedup vs baseline: 1.0031x; 1.0004x over previous
; #define LAS __attribute__((address_space(3)))
; __global__ void __launch_bounds__(512, 2) fwd_mega(Args args) {
;     extern __shared__ __attribute__((aligned(16))) unsigned char lds_raw[];
;     LAS unsigned char* lds = (LAS unsigned char*)lds_raw;
;     cg::grid_group grid = cg::this_grid();
;     const int tid = threadIdx.x, lane = tid & 63, wave = __builtin_amdgcn_readfirstlane(tid >> 6);
;     const int G = gridDim.x, bx = blockIdx.x;
;     const float* x = args.in[0]; const float* mem = args.in[1]; const int* positions = (const int*)args.in[2];
;     float* out = args.out;
;     const int lo = args.ph_lo, hi = args.ph_hi;
;     ...
;     if (args.ph_lo < 0) grid.sync();
_Z8fwd_mega4Args:
	s_nop 0
	s_nop 0
	s_nop 0
	s_nop 0
	s_nop 0
	s_nop 0
	s_mov_b32 s96, s2
	s_load_dwordx4 s[84:87], s[0:1], 0x100
	s_load_dword s2, s[0:1], 0x110
	s_add_u32 s4, s0, 0x108
	s_addc_u32 s5, s1, 0
	v_and_b32_e32 v196, 0x3ff, v0
	s_waitcnt lgkmcnt(0)
	s_cmp_gt_i32 s84, -1
	v_writelane_b32 v249, s2, 0
	s_movk_i32 s2, 0x3ff
	v_readfirstlane_b32 s10, v196
	s_cbranch_scc1 .LBB0_12
	v_lshrrev_b32_e32 v1, 20, v0
	v_lshrrev_b32_e32 v0, 10, v0
	v_or_b32_e32 v0, v0, v1
	v_and_or_b32 v0, v0, s2, v196
	v_cmp_eq_u32_e32 vcc, 0, v0
	s_barrier
	s_and_saveexec_b64 s[2:3], vcc
	s_cbranch_execz .LBB0_11
	buffer_wbl2 sc1
	s_load_dwordx2 s[4:5], s[4:5], 0x58
	s_mov_b64 s[6:7], exec
	v_mbcnt_lo_u32_b32 v0, s6, 0
	v_mbcnt_hi_u32_b32 v0, s7, v0
	v_cmp_eq_u32_e32 vcc, 0, v0
	s_waitcnt lgkmcnt(0)
	s_load_dword s11, s[4:5], 0x28
	s_and_saveexec_b64 s[8:9], vcc
	s_cbranch_execz .LBB0_4
	s_bcnt1_i32_b64 s6, s[6:7]
	v_mov_b32_e32 v1, 0
	v_mov_b32_e32 v2, s6
	global_atomic_add v1, v1, v2, s[4:5] offset:32 sc0
